# converted weights in the G1/G3 slots stored write-through (sc1): no L2 write-back burst at the grid barriers
# baseline (speedup 1.0000x reference)
; __device__ __forceinline__ unsigned pkbf(float lo, float hi) { typedef float f2_t __attribute__((ext_vector_type(2))); typedef __bf16 b2_t __attribute__((ext_vector_type(2))); f2_t v = {lo, hi}; b2_t b = __builtin_convertvector(v, b2_t); return __builtin_bit_cast(unsigned, b); }
; __device__ __forceinline__ void transpose_item(const float* W, int K, int N, bf16* WT, int k0, int n0, int dst_row0, const float* gain_k0, float* scr, int lane) {
;     ...
; #pragma unroll
;     for (int j = 0; j < 8; ++j) { const int n = (lane >> 3) + 8 * j; const float* s = scr + (8 * c) * 65 + n;
;         u32x4 o; o.x = pkbf(s[0 * 65] * g0.x, s[1 * 65] * g0.y); o.y = pkbf(s[2 * 65] * g0.z, s[3 * 65] * g0.w); o.z = pkbf(s[4 * 65] * g1.x, s[5 * 65] * g1.y); o.w = pkbf(s[6 * 65] * g1.z, s[7 * 65] * g1.w);
;         *(u32x4*)(WT + (size_t)(dst_row0 + n) * K + k0 + 8 * c) = o; }
;     asm volatile("s_waitcnt lgkmcnt(0)" ::: "memory");
.LBB0_217:
	ds_read2_b32 v[28:29], v16 offset1:8
	ds_read2_b32 v[30:31], v16 offset0:65 offset1:73
	ds_read2_b32 v[32:33], v16 offset0:130 offset1:138
	ds_read2_b32 v[34:35], v16 offset0:195 offset1:203
	v_add_u32_e32 v46, 0x400, v16
	ds_read2_b32 v[36:37], v46 offset0:4 offset1:12
	ds_read2_b32 v[38:39], v46 offset0:69 offset1:77
	ds_read2_b32 v[40:41], v46 offset0:134 offset1:142
	ds_read2_b32 v[42:43], v46 offset0:199 offset1:207
	s_waitcnt lgkmcnt(7)
	v_mov_b32_e32 v24, v28
	s_waitcnt lgkmcnt(6)
	v_mov_b32_e32 v25, v30
	s_waitcnt lgkmcnt(5)
	v_mov_b32_e32 v26, v32
	s_waitcnt lgkmcnt(4)
	v_mov_b32_e32 v27, v34
	s_mul_hi_i32 s3, s2, 0xe00000
	s_mul_i32 s2, s2, 0xe00000
	v_readlane_b32 s5, v250, 49
	s_waitcnt vmcnt(1)
	v_pk_mul_f32 v[24:25], v[4:5], v[24:25]
	v_pk_mul_f32 v[26:27], v[6:7], v[26:27]
	s_add_u32 s5, s5, s2
	v_readlane_b32 s2, v250, 50
	v_cvt_pk_bf16_f32 v24, v24, v25
	v_cvt_pk_bf16_f32 v25, v26, v27
	s_waitcnt lgkmcnt(3)
	v_mov_b32_e32 v26, v36
	s_waitcnt lgkmcnt(2)
	v_mov_b32_e32 v27, v38
	s_waitcnt lgkmcnt(1)
	v_mov_b32_e32 v44, v40
	s_waitcnt lgkmcnt(0)
	v_mov_b32_e32 v45, v42
	s_addc_u32 s12, s2, s3
	s_lshl_b64 s[2:3], s[6:7], 1
	s_waitcnt vmcnt(0)
	v_pk_mul_f32 v[26:27], v[8:9], v[26:27]
	v_pk_mul_f32 v[44:45], v[10:11], v[44:45]
	s_add_u32 s2, s5, s2
	v_cvt_pk_bf16_f32 v26, v26, v27
	v_cvt_pk_bf16_f32 v27, v44, v45
	v_or_b32_e32 v44, s4, v13
	s_addc_u32 s3, s12, s3
	v_lshlrev_b32_e32 v14, 1, v12
	v_mov_b32_e32 v15, v2
	v_ashrrev_i32_e32 v45, 31, v44
	v_lshl_add_u64 v[14:15], s[2:3], 0, v[14:15]
	v_lshlrev_b64 v[44:45], 12, v[44:45]
	v_lshl_add_u64 v[44:45], v[14:15], 0, v[44:45]
	v_mov_b32_e32 v30, v29
	v_mov_b32_e32 v34, v33
	global_store_dwordx4 v[44:45], v[24:27], off sc1
	v_mov_b32_e32 v38, v37
	v_mov_b32_e32 v42, v41
	v_pk_mul_f32 v[24:25], v[4:5], v[30:31]
	v_pk_mul_f32 v[26:27], v[6:7], v[34:35]
	v_cvt_pk_bf16_f32 v24, v24, v25
	v_cvt_pk_bf16_f32 v25, v26, v27
	v_pk_mul_f32 v[26:27], v[8:9], v[38:39]
	v_pk_mul_f32 v[28:29], v[10:11], v[42:43]
	v_cvt_pk_bf16_f32 v26, v26, v27
	v_cvt_pk_bf16_f32 v27, v28, v29
	v_or_b32_e32 v28, s4, v17
	v_ashrrev_i32_e32 v29, 31, v28
	v_lshlrev_b64 v[28:29], 12, v[28:29]
	v_lshl_add_u64 v[28:29], v[14:15], 0, v[28:29]
	ds_read2_b32 v[30:31], v16 offset0:16 offset1:24
	ds_read2_b32 v[32:33], v16 offset0:81 offset1:89
	global_store_dwordx4 v[28:29], v[24:27], off sc1
	ds_read2_b32 v[28:29], v16 offset0:146 offset1:154
	ds_read2_b32 v[34:35], v16 offset0:211 offset1:219
	ds_read2_b32 v[36:37], v46 offset0:20 offset1:28
	ds_read2_b32 v[38:39], v46 offset0:85 offset1:93
	ds_read2_b32 v[40:41], v46 offset0:150 offset1:158
	ds_read2_b32 v[42:43], v46 offset0:215 offset1:223
	s_waitcnt lgkmcnt(7)
	v_mov_b32_e32 v24, v30
	s_waitcnt lgkmcnt(6)
	v_mov_b32_e32 v25, v32
	s_waitcnt lgkmcnt(5)
	v_mov_b32_e32 v26, v28
	s_waitcnt lgkmcnt(4)
	v_mov_b32_e32 v27, v34
	v_pk_mul_f32 v[24:25], v[4:5], v[24:25]
	v_pk_mul_f32 v[26:27], v[6:7], v[26:27]
	v_cvt_pk_bf16_f32 v24, v24, v25
	v_cvt_pk_bf16_f32 v25, v26, v27
	s_waitcnt lgkmcnt(3)
	v_mov_b32_e32 v26, v36
	s_waitcnt lgkmcnt(2)
	v_mov_b32_e32 v27, v38
	s_waitcnt lgkmcnt(1)
	v_mov_b32_e32 v44, v40
	s_waitcnt lgkmcnt(0)
	v_mov_b32_e32 v45, v42
	v_pk_mul_f32 v[26:27], v[8:9], v[26:27]
	v_pk_mul_f32 v[44:45], v[10:11], v[44:45]
	v_cvt_pk_bf16_f32 v26, v26, v27
	v_cvt_pk_bf16_f32 v27, v44, v45
	v_or_b32_e32 v44, s4, v18
	v_ashrrev_i32_e32 v45, 31, v44
	v_lshlrev_b64 v[44:45], 12, v[44:45]
	v_lshl_add_u64 v[44:45], v[14:15], 0, v[44:45]
	v_mov_b32_e32 v32, v31
	v_mov_b32_e32 v34, v29
	global_store_dwordx4 v[44:45], v[24:27], off sc1
	v_mov_b32_e32 v38, v37
	v_mov_b32_e32 v42, v41
	v_pk_mul_f32 v[24:25], v[4:5], v[32:33]
	v_pk_mul_f32 v[26:27], v[6:7], v[34:35]
	v_cvt_pk_bf16_f32 v24, v24, v25
	v_cvt_pk_bf16_f32 v25, v26, v27
	v_pk_mul_f32 v[26:27], v[8:9], v[38:39]
	v_pk_mul_f32 v[28:29], v[10:11], v[42:43]
	v_cvt_pk_bf16_f32 v26, v26, v27
	v_cvt_pk_bf16_f32 v27, v28, v29
	v_or_b32_e32 v28, s4, v19
	v_ashrrev_i32_e32 v29, 31, v28
	v_lshlrev_b64 v[28:29], 12, v[28:29]
	v_lshl_add_u64 v[28:29], v[14:15], 0, v[28:29]
	ds_read2_b32 v[30:31], v16 offset0:32 offset1:40
	ds_read2_b32 v[32:33], v16 offset0:97 offset1:105
	global_store_dwordx4 v[28:29], v[24:27], off sc1
	ds_read2_b32 v[28:29], v16 offset0:162 offset1:170
	ds_read2_b32 v[34:35], v16 offset0:227 offset1:235
	ds_read2_b32 v[36:37], v46 offset0:36 offset1:44
	ds_read2_b32 v[38:39], v46 offset0:101 offset1:109
	ds_read2_b32 v[40:41], v46 offset0:166 offset1:174
	ds_read2_b32 v[42:43], v46 offset0:231 offset1:239
	s_waitcnt lgkmcnt(7)
; __device__ __forceinline__ unsigned pkbf(float lo, float hi) { typedef float f2_t __attribute__((ext_vector_type(2))); typedef __bf16 b2_t __attribute__((ext_vector_type(2))); f2_t v = {lo, hi}; b2_t b = __builtin_convertvector(v, b2_t); return __builtin_bit_cast(unsigned, b); }
; __device__ __forceinline__ void transpose_item(const float* W, int K, int N, bf16* WT, int k0, int n0, int dst_row0, const float* gain_k0, float* scr, int lane) {
;     ...
; #pragma unroll
;     for (int j = 0; j < 8; ++j) { const int n = (lane >> 3) + 8 * j; const float* s = scr + (8 * c) * 65 + n;
;         u32x4 o; o.x = pkbf(s[0 * 65] * g0.x, s[1 * 65] * g0.y); o.y = pkbf(s[2 * 65] * g0.z, s[3 * 65] * g0.w); o.z = pkbf(s[4 * 65] * g1.x, s[5 * 65] * g1.y); o.w = pkbf(s[6 * 65] * g1.z, s[7 * 65] * g1.w);
;         *(u32x4*)(WT + (size_t)(dst_row0 + n) * K + k0 + 8 * c) = o; }
;     asm volatile("s_waitcnt lgkmcnt(0)" ::: "memory");
	v_mov_b32_e32 v24, v30
	s_waitcnt lgkmcnt(6)
	v_mov_b32_e32 v25, v32
	s_waitcnt lgkmcnt(5)
	v_mov_b32_e32 v26, v28
	s_waitcnt lgkmcnt(4)
	v_mov_b32_e32 v27, v34
	v_pk_mul_f32 v[24:25], v[4:5], v[24:25]
	v_pk_mul_f32 v[26:27], v[6:7], v[26:27]
	v_cvt_pk_bf16_f32 v24, v24, v25
	v_cvt_pk_bf16_f32 v25, v26, v27
	s_waitcnt lgkmcnt(3)
	v_mov_b32_e32 v26, v36
	s_waitcnt lgkmcnt(2)
	v_mov_b32_e32 v27, v38
	s_waitcnt lgkmcnt(1)
	v_mov_b32_e32 v44, v40
	s_waitcnt lgkmcnt(0)
	v_mov_b32_e32 v45, v42
	v_pk_mul_f32 v[26:27], v[8:9], v[26:27]
	v_pk_mul_f32 v[44:45], v[10:11], v[44:45]
	v_cvt_pk_bf16_f32 v26, v26, v27
	v_cvt_pk_bf16_f32 v27, v44, v45
	v_or_b32_e32 v44, s4, v20
	v_ashrrev_i32_e32 v45, 31, v44
	v_lshlrev_b64 v[44:45], 12, v[44:45]
	v_lshl_add_u64 v[44:45], v[14:15], 0, v[44:45]
	v_mov_b32_e32 v32, v31
	v_mov_b32_e32 v34, v29
	global_store_dwordx4 v[44:45], v[24:27], off sc1
	v_mov_b32_e32 v38, v37
	v_mov_b32_e32 v42, v41
	v_pk_mul_f32 v[24:25], v[4:5], v[32:33]
	v_pk_mul_f32 v[26:27], v[6:7], v[34:35]
	v_cvt_pk_bf16_f32 v24, v24, v25
	v_cvt_pk_bf16_f32 v25, v26, v27
	v_pk_mul_f32 v[26:27], v[8:9], v[38:39]
	v_pk_mul_f32 v[28:29], v[10:11], v[42:43]
	v_cvt_pk_bf16_f32 v26, v26, v27
	v_cvt_pk_bf16_f32 v27, v28, v29
	v_or_b32_e32 v28, s4, v21
	v_ashrrev_i32_e32 v29, 31, v28
	v_lshlrev_b64 v[28:29], 12, v[28:29]
	v_lshl_add_u64 v[28:29], v[14:15], 0, v[28:29]
	ds_read2_b32 v[30:31], v16 offset0:48 offset1:56
	ds_read2_b32 v[32:33], v16 offset0:113 offset1:121
	global_store_dwordx4 v[28:29], v[24:27], off sc1
	ds_read2_b32 v[28:29], v16 offset0:178 offset1:186
	ds_read2_b32 v[34:35], v16 offset0:243 offset1:251
	ds_read2_b32 v[36:37], v46 offset0:52 offset1:60
	ds_read2_b32 v[38:39], v46 offset0:117 offset1:125
	ds_read2_b32 v[40:41], v46 offset0:182 offset1:190
	ds_read2_b32 v[42:43], v46 offset0:247 offset1:255
	s_waitcnt lgkmcnt(7)
	v_mov_b32_e32 v24, v30
	s_waitcnt lgkmcnt(6)
	v_mov_b32_e32 v25, v32
	s_waitcnt lgkmcnt(5)
	v_mov_b32_e32 v26, v28
	s_waitcnt lgkmcnt(4)
	v_mov_b32_e32 v27, v34
	v_pk_mul_f32 v[24:25], v[4:5], v[24:25]
	v_pk_mul_f32 v[26:27], v[6:7], v[26:27]
	v_mov_b32_e32 v32, v31
	v_mov_b32_e32 v34, v29
	v_cvt_pk_bf16_f32 v24, v24, v25
	v_cvt_pk_bf16_f32 v25, v26, v27
	s_waitcnt lgkmcnt(3)
	v_mov_b32_e32 v26, v36
	s_waitcnt lgkmcnt(2)
	v_mov_b32_e32 v27, v38
	s_waitcnt lgkmcnt(1)
	v_mov_b32_e32 v44, v40
	s_waitcnt lgkmcnt(0)
	v_mov_b32_e32 v45, v42
	v_pk_mul_f32 v[4:5], v[4:5], v[32:33]
	v_pk_mul_f32 v[6:7], v[6:7], v[34:35]
	v_mov_b32_e32 v38, v37
	v_mov_b32_e32 v42, v41
	v_pk_mul_f32 v[26:27], v[8:9], v[26:27]
	v_pk_mul_f32 v[44:45], v[10:11], v[44:45]
	v_cvt_pk_bf16_f32 v4, v4, v5
	v_cvt_pk_bf16_f32 v5, v6, v7
	v_pk_mul_f32 v[6:7], v[8:9], v[38:39]
	v_pk_mul_f32 v[8:9], v[10:11], v[42:43]
	v_cvt_pk_bf16_f32 v26, v26, v27
	v_cvt_pk_bf16_f32 v27, v44, v45
	v_or_b32_e32 v44, s4, v22
	v_cvt_pk_bf16_f32 v6, v6, v7
	v_cvt_pk_bf16_f32 v7, v8, v9
	v_or_b32_e32 v8, s4, v23
	v_ashrrev_i32_e32 v45, 31, v44
	v_ashrrev_i32_e32 v9, 31, v8
	v_lshlrev_b64 v[44:45], 12, v[44:45]
	v_lshlrev_b64 v[8:9], 12, v[8:9]
	v_lshl_add_u64 v[44:45], v[14:15], 0, v[44:45]
	v_lshl_add_u64 v[8:9], v[14:15], 0, v[8:9]
	global_store_dwordx4 v[44:45], v[24:27], off sc1
	global_store_dwordx4 v[8:9], v[4:7], off sc1
	s_waitcnt lgkmcnt(0)

; __device__ __forceinline__ void transpose_item(const float* W, int K, int N, bf16* WT, int k0, int n0, int dst_row0, const float* gain_k0, float* scr, int lane) {
;     ...
;     const float* src = W + (size_t)(k0 + r) * N + n0 + 4 * q;
;     f32x4 v[16];
; #pragma unroll
;     for (int i = 0; i < 16; ++i) v[i] = __builtin_nontemporal_load((const f32x4*)(src + (size_t)(4 * i) * N));
; #pragma unroll
;     for (int i = 0; i < 16; ++i) { float* d = scr + (4 * i + r) * 65 + 4 * q; d[0] = v[i].x; d[1] = v[i].y; d[2] = v[i].z; d[3] = v[i].w; }
;     asm volatile("s_waitcnt lgkmcnt(0)" ::: "memory");
; __device__ __forceinline__ void convert_items(const Args& A, unsigned char* ws, int g0, int g1, int w, int nw, float* scr, int lane) {
;     for (int it = g0 + w; it < g1; it += nw) {
;         const int l = it / PER_LAYER; int r = it % PER_LAYER;
;         if (r < I_IN) { const int nb = INW / 64, kb = r / nb, n0 = 64 * (r % nb); transpose_item(A.w_in + (size_t)l * DM * INW, DM, INW, (bf16*)(ws + WS_WIN + l * SZ_WIN), 64 * kb, n0, n0, A.norm1_g + l * DM + 64 * kb, scr, lane); continue; } r -= I_IN;
;         if (r < I_OUT) { const int nb = DM / 64, kb = r / nb, n0 = 64 * (r % nb); transpose_item(A.w_out + (size_t)l * DM * DM, DM, DM, (bf16*)(ws + WS_WOUT + l * SZ_WOUT), 64 * kb, n0, n0, (kb < 16 ? A.out_norm_a + l * 1024 + 64 * kb : A.out_norm_b + l * 1024 + 64 * (kb - 16)), scr, lane); continue; } r -= I_OUT;
;         if (r < I_G) { const int nb = DFF / 64, kb = r / nb, n0 = 64 * (r % nb); transpose_item(A.w_gate + (size_t)l * DM * DFF, DM, DFF, (bf16*)(ws + WS_WGU + l * SZ_WGU), 64 * kb, n0, 256 * (n0 / 128) + (n0 % 128), A.norm2_g + l * DM + 64 * kb, scr, lane); continue; } r -= I_G;
;         if (r < I_G) { const int nb = DFF / 64, kb = r / nb, n0 = 64 * (r % nb); transpose_item(A.w_up + (size_t)l * DM * DFF, DM, DFF, (bf16*)(ws + WS_WGU + l * SZ_WGU), 64 * kb, n0, 256 * (n0 / 128) + 128 + (n0 % 128), A.norm2_g + l * DM + 64 * kb, scr, lane); continue; } r -= I_G;
;         { const int nb = DM / 64, kb = r / nb, n0 = 64 * (r % nb); transpose_item(A.w_down + (size_t)l * DFF * DM, DFF, DM, (bf16*)(ws + WS_WDN + l * SZ_WDN), 64 * kb, n0, n0, nullptr, scr, lane); }
.LBB0_219:
	s_mul_hi_i32 s2, s9, 0x2e8ba2e9
	s_lshr_b32 s3, s2, 31
	s_ashr_i32 s2, s2, 11
	s_add_i32 s2, s2, s3
	s_mul_i32 s3, s2, 0xffffd400
	s_add_i32 s6, s9, s3
	s_cmpk_gt_i32 s6, 0x6ff
	s_mov_b64 s[4:5], -1
	s_cbranch_scc0 .LBB0_246
	s_cmpk_gt_u32 s6, 0xaff
	s_cbranch_scc0 .LBB0_240
	s_cmpk_gt_u32 s6, 0x15ff
	s_cbranch_scc0 .LBB0_232
	s_cmpk_gt_u32 s6, 0x20ff
	s_cbranch_scc0 .LBB0_224
	s_and_b32 s3, s10, 0x7c0
	s_mul_i32 s5, s2, 0x2c00000
	v_readlane_b32 s12, v250, 1
	s_mul_hi_i32 s4, s2, 0x2c00000
	v_readlane_b32 s13, v250, 2
	s_add_u32 s12, s12, s5
	s_addc_u32 s13, s13, s4
	s_mul_i32 s5, s2, 0x1600000
	v_readlane_b32 s7, v250, 63
	v_readlane_b32 s14, v250, 3
	s_mul_hi_i32 s4, s2, 0x1600000
	s_add_u32 s7, s7, s5
	v_readlane_b32 s5, v249, 0
	s_addc_u32 s14, s5, s4
	s_mul_i32 s4, s2, 0xffffa800
	s_add_i32 s4, s11, s4
	s_and_b32 s4, s4, 0x7fffffc0
	s_addk_i32 s4, 0xbe00
	v_or_b32_e32 v4, s4, v1
	v_mov_b32_e32 v5, v2
	v_lshlrev_b64 v[4:5], 13, v[4:5]
	v_lshl_add_u64 v[4:5], s[12:13], 0, v[4:5]
	s_lshl_b32 s76, s3, 2
	v_lshl_add_u64 v[4:5], v[4:5], 0, s[76:77]
	v_lshlrev_b32_e32 v6, 2, v0
	v_mov_b32_e32 v7, v2
	v_lshl_add_u64 v[14:15], v[4:5], 0, v[6:7]
	s_mov_b32 s5, 0x8000
	v_add_co_u32_e32 v8, vcc, s5, v14
	s_mov_b32 s5, 0x10000
	s_nop 0
	v_addc_co_u32_e32 v9, vcc, 0, v15, vcc
	v_add_co_u32_e32 v24, vcc, s5, v14
	global_load_dwordx4 v[4:7], v[14:15], off nt
	s_nop 0
	global_load_dwordx4 v[8:11], v[8:9], off nt
	v_addc_co_u32_e32 v25, vcc, 0, v15, vcc
	s_mov_b32 s5, 0x18000
	v_add_co_u32_e32 v28, vcc, s5, v14
	s_mov_b32 s5, 0x20000
	s_nop 0
	v_addc_co_u32_e32 v29, vcc, 0, v15, vcc
	global_load_dwordx4 v[24:27], v[24:25], off nt
	s_nop 0
	global_load_dwordx4 v[28:31], v[28:29], off nt
	v_add_co_u32_e32 v32, vcc, s5, v14
	s_mov_b32 s5, 0x28000
	s_nop 0
	v_addc_co_u32_e32 v33, vcc, 0, v15, vcc
	v_add_co_u32_e32 v36, vcc, s5, v14
	s_mov_b32 s5, 0x30000
	s_nop 0
	v_addc_co_u32_e32 v37, vcc, 0, v15, vcc
	global_load_dwordx4 v[32:35], v[32:33], off nt
	s_nop 0
	global_load_dwordx4 v[36:39], v[36:37], off nt
	v_add_co_u32_e32 v40, vcc, s5, v14
	s_mov_b32 s5, 0x38000
	s_nop 0
	v_addc_co_u32_e32 v41, vcc, 0, v15, vcc
	v_add_co_u32_e32 v44, vcc, s5, v14
	s_mov_b32 s5, 0x40000
	s_nop 0
	v_addc_co_u32_e32 v45, vcc, 0, v15, vcc
	global_load_dwordx4 v[40:43], v[40:41], off nt
	s_nop 0
	global_load_dwordx4 v[44:47], v[44:45], off nt
	v_add_co_u32_e32 v48, vcc, s5, v14
	s_mov_b32 s5, 0x48000
	s_nop 0
	v_addc_co_u32_e32 v49, vcc, 0, v15, vcc
	v_add_co_u32_e32 v52, vcc, s5, v14
	s_mov_b32 s5, 0x50000
	s_nop 0
	v_addc_co_u32_e32 v53, vcc, 0, v15, vcc
	global_load_dwordx4 v[48:51], v[48:49], off nt
	s_nop 0
	global_load_dwordx4 v[52:55], v[52:53], off nt
	v_add_co_u32_e32 v56, vcc, s5, v14
	s_mov_b32 s5, 0x58000
	s_nop 0
	v_addc_co_u32_e32 v57, vcc, 0, v15, vcc
	v_add_co_u32_e32 v60, vcc, s5, v14
	s_mov_b32 s5, 0x60000
	s_nop 0
	v_addc_co_u32_e32 v61, vcc, 0, v15, vcc
	global_load_dwordx4 v[56:59], v[56:57], off nt
	s_nop 0
	global_load_dwordx4 v[60:63], v[60:61], off nt
	v_add_co_u32_e32 v64, vcc, s5, v14
	s_mov_b32 s5, 0x68000
	s_nop 0
	v_addc_co_u32_e32 v65, vcc, 0, v15, vcc
	global_load_dwordx4 v[64:67], v[64:65], off nt
	v_add_co_u32_e32 v68, vcc, s5, v14
	s_mov_b32 s5, 0x70000
	s_nop 0
	v_addc_co_u32_e32 v69, vcc, 0, v15, vcc
	global_load_dwordx4 v[68:71], v[68:69], off nt
	v_add_co_u32_e32 v72, vcc, s5, v14
	s_mov_b32 s5, 0x78000
	s_nop 0
	v_addc_co_u32_e32 v73, vcc, 0, v15, vcc
	global_load_dwordx4 v[72:75], v[72:73], off nt
	v_add_co_u32_e32 v14, vcc, s5, v14
	s_mov_b32 s5, s77
	s_nop 0
	v_addc_co_u32_e32 v15, vcc, 0, v15, vcc
	global_load_dwordx4 v[76:79], v[14:15], off nt
	s_waitcnt vmcnt(15)
	ds_write2_b32 v3, v4, v5 offset1:1
	ds_write2_b32 v3, v6, v7 offset0:2 offset1:3
	v_add_u32_e32 v4, 0x410, v3
	s_waitcnt vmcnt(14)
	ds_write2_b32 v4, v8, v9 offset1:1
	v_add_u32_e32 v4, 0x418, v3
	ds_write2_b32 v4, v10, v11 offset1:1
	v_add_u32_e32 v4, 0x820, v3
	s_lshl_b64 s[4:5], s[4:5], 1
	s_add_u32 s4, s7, s4
	s_addc_u32 s5, s14, s5
	s_waitcnt vmcnt(13)
	ds_write2_b32 v4, v24, v25 offset1:1
	v_add_u32_e32 v4, 0x828, v3
	ds_write2_b32 v4, v26, v27 offset1:1
	v_add_u32_e32 v4, 0xc30, v3
	s_waitcnt vmcnt(12)
	ds_write2_b32 v4, v28, v29 offset1:1
	v_add_u32_e32 v4, 0xc38, v3
	ds_write2_b32 v4, v30, v31 offset1:1
	v_add_u32_e32 v4, 0x1040, v3
	v_mov_b32_e32 v5, v2
	v_readlane_b32 s15, v250, 4
	s_waitcnt vmcnt(11)
	ds_write2_b32 v4, v32, v33 offset1:1
	v_add_u32_e32 v4, 0x1048, v3
	ds_write2_b32 v4, v34, v35 offset1:1
	v_add_u32_e32 v4, 0x1450, v3
	s_waitcnt vmcnt(10)
	ds_write2_b32 v4, v36, v37 offset1:1
	v_add_u32_e32 v4, 0x1458, v3
	ds_write2_b32 v4, v38, v39 offset1:1
	v_add_u32_e32 v4, 0x1860, v3
	v_add_u32_e32 v38, 0x400, v16
	v_mov_b32_e32 v37, v2
	s_waitcnt vmcnt(9)
	ds_write2_b32 v4, v40, v41 offset1:1
	v_add_u32_e32 v4, 0x1868, v3
	ds_write2_b32 v4, v42, v43 offset1:1
	v_add_u32_e32 v4, 0x1c70, v3
	s_waitcnt vmcnt(8)
	ds_write2_b32 v4, v44, v45 offset1:1
	v_add_u32_e32 v4, 0x1c78, v3
	ds_write2_b32 v4, v46, v47 offset1:1
	v_add_u32_e32 v4, 0x2080, v3
	s_waitcnt vmcnt(7)
	ds_write2_b32 v4, v48, v49 offset1:1
	v_add_u32_e32 v4, 0x2088, v3
	ds_write2_b32 v4, v50, v51 offset1:1
	v_add_u32_e32 v4, 0x2490, v3
	s_waitcnt vmcnt(6)
	ds_write2_b32 v4, v52, v53 offset1:1
	v_add_u32_e32 v4, 0x2498, v3
	ds_write2_b32 v4, v54, v55 offset1:1
	v_add_u32_e32 v4, 0x28a0, v3
	s_waitcnt vmcnt(5)
	ds_write2_b32 v4, v56, v57 offset1:1
	v_add_u32_e32 v4, 0x28a8, v3
	ds_write2_b32 v4, v58, v59 offset1:1
	v_add_u32_e32 v4, 0x2cb0, v3
	s_waitcnt vmcnt(4)
; __device__ __forceinline__ unsigned pkbf(float lo, float hi) { typedef float f2_t __attribute__((ext_vector_type(2))); typedef __bf16 b2_t __attribute__((ext_vector_type(2))); f2_t v = {lo, hi}; b2_t b = __builtin_convertvector(v, b2_t); return __builtin_bit_cast(unsigned, b); }
; __device__ __forceinline__ void transpose_item(const float* W, int K, int N, bf16* WT, int k0, int n0, int dst_row0, const float* gain_k0, float* scr, int lane) {
;     ...
;     asm volatile("s_waitcnt lgkmcnt(0)" ::: "memory");
;     const int c = lane & 7;
;     f32x4 g0 = (f32x4){1.f, 1.f, 1.f, 1.f}, g1 = g0;
;     if (gain_k0) { g0 = *(const f32x4*)(gain_k0 + 8 * c); g1 = *(const f32x4*)(gain_k0 + 8 * c + 4); }
; #pragma unroll
;     for (int j = 0; j < 8; ++j) { const int n = (lane >> 3) + 8 * j; const float* s = scr + (8 * c) * 65 + n;
;         u32x4 o; o.x = pkbf(s[0 * 65] * g0.x, s[1 * 65] * g0.y); o.y = pkbf(s[2 * 65] * g0.z, s[3 * 65] * g0.w); o.z = pkbf(s[4 * 65] * g1.x, s[5 * 65] * g1.y); o.w = pkbf(s[6 * 65] * g1.z, s[7 * 65] * g1.w);
;         *(u32x4*)(WT + (size_t)(dst_row0 + n) * K + k0 + 8 * c) = o; }
;     asm volatile("s_waitcnt lgkmcnt(0)" ::: "memory");
; __device__ __forceinline__ void convert_items(const Args& A, unsigned char* ws, int g0, int g1, int w, int nw, float* scr, int lane) {
;     ...
;         { const int nb = DM / 64, kb = r / nb, n0 = 64 * (r % nb); transpose_item(A.w_down + (size_t)l * DFF * DM, DFF, DM, (bf16*)(ws + WS_WDN + l * SZ_WDN), 64 * kb, n0, n0, nullptr, scr, lane); }
	ds_write2_b32 v4, v60, v61 offset1:1
	v_add_u32_e32 v4, 0x2cb8, v3
	ds_write2_b32 v4, v62, v63 offset1:1
	v_add_u32_e32 v4, 0x30c0, v3
	s_waitcnt vmcnt(3)
	ds_write2_b32 v4, v64, v65 offset1:1
	v_add_u32_e32 v4, 0x30c8, v3
	ds_write2_b32 v4, v66, v67 offset1:1
	v_add_u32_e32 v4, 0x34d0, v3
	s_waitcnt vmcnt(2)
	ds_write2_b32 v4, v68, v69 offset1:1
	v_add_u32_e32 v4, 0x34d8, v3
	ds_write2_b32 v4, v70, v71 offset1:1
	v_add_u32_e32 v4, 0x38e0, v3
	s_waitcnt vmcnt(1)
	ds_write2_b32 v4, v72, v73 offset1:1
	v_add_u32_e32 v4, 0x38e8, v3
	ds_write2_b32 v4, v74, v75 offset1:1
	v_add_u32_e32 v4, 0x3cf0, v3
	s_waitcnt vmcnt(0)
	ds_write2_b32 v4, v76, v77 offset1:1
	v_add_u32_e32 v4, 0x3cf8, v3
	ds_write2_b32 v4, v78, v79 offset1:1
	s_waitcnt lgkmcnt(0)
	ds_read2_b32 v[8:9], v16 offset0:65 offset1:73
	ds_read2_b32 v[10:11], v16 offset1:8
	ds_read2_b32 v[14:15], v16 offset0:130 offset1:138
	ds_read2_b32 v[24:25], v16 offset0:195 offset1:203
	ds_read2_b32 v[26:27], v38 offset0:4 offset1:12
	ds_read2_b32 v[28:29], v38 offset0:69 offset1:77
	ds_read2_b32 v[30:31], v38 offset0:134 offset1:142
	ds_read2_b32 v[32:33], v38 offset0:199 offset1:207
	v_lshlrev_b32_e32 v4, 1, v12
	v_lshl_add_u64 v[34:35], s[4:5], 0, v[4:5]
	s_waitcnt lgkmcnt(6)
	v_cvt_pk_bf16_f32 v4, v10, v8
	v_or_b32_e32 v8, s3, v13
	v_mul_u32_u24_e32 v8, 0x1600, v8
	v_lshlrev_b32_e32 v36, 1, v8
	s_waitcnt lgkmcnt(4)
	v_cvt_pk_bf16_f32 v5, v14, v24
	s_waitcnt lgkmcnt(2)
	v_cvt_pk_bf16_f32 v6, v26, v28
	s_waitcnt lgkmcnt(0)
	v_cvt_pk_bf16_f32 v7, v30, v32
	v_lshl_add_u64 v[36:37], v[34:35], 0, v[36:37]
	v_or_b32_e32 v8, s3, v17
	global_store_dwordx4 v[36:37], v[4:7], off sc1
	v_mul_u32_u24_e32 v8, 0x1600, v8
	v_lshlrev_b32_e32 v8, 1, v8
	v_cvt_pk_bf16_f32 v4, v11, v9
	v_cvt_pk_bf16_f32 v5, v15, v25
	v_cvt_pk_bf16_f32 v6, v27, v29
	v_cvt_pk_bf16_f32 v7, v31, v33
	v_mov_b32_e32 v9, v2
	ds_read2_b32 v[10:11], v16 offset0:16 offset1:24
	ds_read2_b32 v[14:15], v16 offset0:81 offset1:89
	ds_read2_b32 v[24:25], v16 offset0:146 offset1:154
	ds_read2_b32 v[26:27], v16 offset0:211 offset1:219
	ds_read2_b32 v[28:29], v38 offset0:20 offset1:28
	ds_read2_b32 v[30:31], v38 offset0:85 offset1:93
	ds_read2_b32 v[32:33], v38 offset0:150 offset1:158
	ds_read2_b32 v[36:37], v38 offset0:215 offset1:223
	v_lshl_add_u64 v[8:9], v[34:35], 0, v[8:9]
	global_store_dwordx4 v[8:9], v[4:7], off sc1
	v_or_b32_e32 v8, s3, v18
	v_mul_u32_u24_e32 v8, 0x1600, v8
	v_lshlrev_b32_e32 v8, 1, v8
	v_mov_b32_e32 v9, v2
	s_waitcnt lgkmcnt(6)
	v_cvt_pk_bf16_f32 v4, v10, v14
	s_waitcnt lgkmcnt(4)
	v_cvt_pk_bf16_f32 v5, v24, v26
	s_waitcnt lgkmcnt(2)
	v_cvt_pk_bf16_f32 v6, v28, v30
	s_waitcnt lgkmcnt(0)
	v_cvt_pk_bf16_f32 v7, v32, v36
	v_lshl_add_u64 v[8:9], v[34:35], 0, v[8:9]
	global_store_dwordx4 v[8:9], v[4:7], off sc1
	v_or_b32_e32 v8, s3, v19
	v_mul_u32_u24_e32 v8, 0x1600, v8
	v_cvt_pk_bf16_f32 v4, v11, v15
	v_cvt_pk_bf16_f32 v5, v25, v27
	v_cvt_pk_bf16_f32 v6, v29, v31
	v_cvt_pk_bf16_f32 v7, v33, v37
	v_lshlrev_b32_e32 v8, 1, v8
	v_mov_b32_e32 v9, v2
	ds_read2_b32 v[10:11], v16 offset0:32 offset1:40
	ds_read2_b32 v[14:15], v16 offset0:97 offset1:105
	ds_read2_b32 v[24:25], v16 offset0:162 offset1:170
	ds_read2_b32 v[26:27], v16 offset0:227 offset1:235
	ds_read2_b32 v[28:29], v38 offset0:36 offset1:44
	ds_read2_b32 v[30:31], v38 offset0:101 offset1:109
	ds_read2_b32 v[32:33], v38 offset0:166 offset1:174
	ds_read2_b32 v[36:37], v38 offset0:231 offset1:239
	v_lshl_add_u64 v[8:9], v[34:35], 0, v[8:9]
	global_store_dwordx4 v[8:9], v[4:7], off sc1
	v_or_b32_e32 v8, s3, v20
	v_mul_u32_u24_e32 v8, 0x1600, v8
	v_lshlrev_b32_e32 v8, 1, v8
	v_mov_b32_e32 v9, v2
	s_waitcnt lgkmcnt(6)
	v_cvt_pk_bf16_f32 v4, v10, v14
	s_waitcnt lgkmcnt(4)
	v_cvt_pk_bf16_f32 v5, v24, v26
	s_waitcnt lgkmcnt(2)
	v_cvt_pk_bf16_f32 v6, v28, v30
	s_waitcnt lgkmcnt(0)
	v_cvt_pk_bf16_f32 v7, v32, v36
	v_lshl_add_u64 v[8:9], v[34:35], 0, v[8:9]
	global_store_dwordx4 v[8:9], v[4:7], off sc1
	v_or_b32_e32 v8, s3, v21
	v_mul_u32_u24_e32 v8, 0x1600, v8
	v_cvt_pk_bf16_f32 v4, v11, v15
	v_cvt_pk_bf16_f32 v5, v25, v27
	v_cvt_pk_bf16_f32 v6, v29, v31
	v_cvt_pk_bf16_f32 v7, v33, v37
	v_lshlrev_b32_e32 v8, 1, v8
	v_mov_b32_e32 v9, v2
	ds_read2_b32 v[10:11], v16 offset0:48 offset1:56
	ds_read2_b32 v[14:15], v16 offset0:113 offset1:121
	ds_read2_b32 v[24:25], v16 offset0:178 offset1:186
	ds_read2_b32 v[26:27], v16 offset0:243 offset1:251
	ds_read2_b32 v[28:29], v38 offset0:52 offset1:60
	ds_read2_b32 v[30:31], v38 offset0:117 offset1:125
	ds_read2_b32 v[32:33], v38 offset0:182 offset1:190
	ds_read2_b32 v[36:37], v38 offset0:247 offset1:255
	v_lshl_add_u64 v[8:9], v[34:35], 0, v[8:9]
	global_store_dwordx4 v[8:9], v[4:7], off sc1
	v_or_b32_e32 v8, s3, v22
	v_mul_u32_u24_e32 v8, 0x1600, v8
	v_lshlrev_b32_e32 v8, 1, v8
	v_mov_b32_e32 v9, v2
	s_waitcnt lgkmcnt(6)
	v_cvt_pk_bf16_f32 v4, v10, v14
	s_waitcnt lgkmcnt(4)
	v_cvt_pk_bf16_f32 v5, v24, v26
	s_waitcnt lgkmcnt(2)
	v_cvt_pk_bf16_f32 v6, v28, v30
	s_waitcnt lgkmcnt(0)
	v_cvt_pk_bf16_f32 v7, v32, v36
	v_lshl_add_u64 v[8:9], v[34:35], 0, v[8:9]
	global_store_dwordx4 v[8:9], v[4:7], off sc1
	v_or_b32_e32 v8, s3, v23
	v_mul_u32_u24_e32 v8, 0x1600, v8
	v_lshlrev_b32_e32 v8, 1, v8
	v_mov_b32_e32 v9, v2
	v_cvt_pk_bf16_f32 v4, v11, v15
	v_cvt_pk_bf16_f32 v5, v25, v27
	v_cvt_pk_bf16_f32 v6, v29, v31
	v_cvt_pk_bf16_f32 v7, v33, v37
	v_lshl_add_u64 v[8:9], v[34:35], 0, v[8:9]
	global_store_dwordx4 v[8:9], v[4:7], off sc1
	s_waitcnt lgkmcnt(0)
	s_mov_b64 s[4:5], 0

; __device__ __forceinline__ unsigned pkbf(float lo, float hi) { typedef float f2_t __attribute__((ext_vector_type(2))); typedef __bf16 b2_t __attribute__((ext_vector_type(2))); f2_t v = {lo, hi}; b2_t b = __builtin_convertvector(v, b2_t); return __builtin_bit_cast(unsigned, b); }
; __device__ __forceinline__ void transpose_item(const float* W, int K, int N, bf16* WT, int k0, int n0, int dst_row0, const float* gain_k0, float* scr, int lane) {
;     ...
; #pragma unroll
;     for (int j = 0; j < 8; ++j) { const int n = (lane >> 3) + 8 * j; const float* s = scr + (8 * c) * 65 + n;
;         u32x4 o; o.x = pkbf(s[0 * 65] * g0.x, s[1 * 65] * g0.y); o.y = pkbf(s[2 * 65] * g0.z, s[3 * 65] * g0.w); o.z = pkbf(s[4 * 65] * g1.x, s[5 * 65] * g1.y); o.w = pkbf(s[6 * 65] * g1.z, s[7 * 65] * g1.w);
;         *(u32x4*)(WT + (size_t)(dst_row0 + n) * K + k0 + 8 * c) = o; }
;     asm volatile("s_waitcnt lgkmcnt(0)" ::: "memory");
; __device__ __forceinline__ void convert_items(const Args& A, unsigned char* ws, int g0, int g1, int w, int nw, float* scr, int lane) {
;     ...
;         if (r < I_G) { const int nb = DFF / 64, kb = r / nb, n0 = 64 * (r % nb); transpose_item(A.w_up + (size_t)l * DM * DFF, DM, DFF, (bf16*)(ws + WS_WGU + l * SZ_WGU), 64 * kb, n0, 256 * (n0 / 128) + 128 + (n0 % 128), A.norm2_g + l * DM + 64 * kb, scr, lane); continue; } r -= I_G;
.LBB0_230:
	ds_read2_b32 v[28:29], v16 offset1:8
	ds_read2_b32 v[30:31], v16 offset0:65 offset1:73
	ds_read2_b32 v[32:33], v16 offset0:130 offset1:138
	ds_read2_b32 v[34:35], v16 offset0:195 offset1:203
	v_add_u32_e32 v46, 0x400, v16
	s_lshl_b32 s4, s3, 6
	v_readlane_b32 s5, v249, 1
	ds_read2_b32 v[36:37], v46 offset0:4 offset1:12
	ds_read2_b32 v[38:39], v46 offset0:69 offset1:77
	ds_read2_b32 v[40:41], v46 offset0:134 offset1:142
	ds_read2_b32 v[42:43], v46 offset0:199 offset1:207
	s_add_u32 s5, s5, s12
	v_readlane_b32 s12, v249, 2
	s_addc_u32 s7, s12, s7
	s_lshl_b32 s3, s3, 7
	s_and_b32 s4, s4, 64
	s_or_b32 s3, s4, s3
	s_waitcnt lgkmcnt(7)
	v_mov_b32_e32 v24, v28
	s_waitcnt lgkmcnt(6)
	v_mov_b32_e32 v25, v30
	s_waitcnt lgkmcnt(5)
	v_mov_b32_e32 v26, v32
	s_waitcnt lgkmcnt(4)
	v_mov_b32_e32 v27, v34
	s_bitset1_b32 s3, 7
	s_lshl_b32 s4, s13, 1
	s_waitcnt vmcnt(1)
	v_pk_mul_f32 v[24:25], v[8:9], v[24:25]
	v_pk_mul_f32 v[26:27], v[10:11], v[26:27]
	s_add_u32 s4, s5, s4
	v_cvt_pk_bf16_f32 v24, v24, v25
	v_cvt_pk_bf16_f32 v25, v26, v27
	s_waitcnt lgkmcnt(3)
	v_mov_b32_e32 v26, v36
	s_waitcnt lgkmcnt(2)
	v_mov_b32_e32 v27, v38
	s_waitcnt lgkmcnt(1)
	v_mov_b32_e32 v44, v40
	s_waitcnt lgkmcnt(0)
	v_mov_b32_e32 v45, v42
	s_addc_u32 s5, s7, 0
	v_lshlrev_b32_e32 v14, 1, v12
	v_mov_b32_e32 v15, v2
	s_waitcnt vmcnt(0)
	v_pk_mul_f32 v[26:27], v[4:5], v[26:27]
	v_pk_mul_f32 v[44:45], v[6:7], v[44:45]
	v_or_b32_e32 v28, s3, v13
	v_lshl_add_u64 v[14:15], s[4:5], 0, v[14:15]
	v_cvt_pk_bf16_f32 v26, v26, v27
	v_cvt_pk_bf16_f32 v27, v44, v45
	v_lshlrev_b32_e32 v44, 12, v28
	v_mov_b32_e32 v45, v2
	v_lshl_add_u64 v[44:45], v[14:15], 0, v[44:45]
	v_mov_b32_e32 v30, v29
	v_mov_b32_e32 v34, v33
	global_store_dwordx4 v[44:45], v[24:27], off sc1
	v_mov_b32_e32 v38, v37
	v_mov_b32_e32 v42, v41
	v_pk_mul_f32 v[24:25], v[8:9], v[30:31]
	v_pk_mul_f32 v[26:27], v[10:11], v[34:35]
	v_cvt_pk_bf16_f32 v24, v24, v25
	v_cvt_pk_bf16_f32 v25, v26, v27
	v_pk_mul_f32 v[26:27], v[4:5], v[38:39]
	v_pk_mul_f32 v[28:29], v[6:7], v[42:43]
	v_cvt_pk_bf16_f32 v26, v26, v27
	v_cvt_pk_bf16_f32 v27, v28, v29
	v_or_b32_e32 v28, s3, v17
	v_lshlrev_b32_e32 v28, 12, v28
	v_mov_b32_e32 v29, v2
	v_lshl_add_u64 v[28:29], v[14:15], 0, v[28:29]
	ds_read2_b32 v[30:31], v16 offset0:16 offset1:24
	ds_read2_b32 v[32:33], v16 offset0:81 offset1:89
	global_store_dwordx4 v[28:29], v[24:27], off sc1
	ds_read2_b32 v[28:29], v16 offset0:146 offset1:154
	ds_read2_b32 v[34:35], v16 offset0:211 offset1:219
	ds_read2_b32 v[36:37], v46 offset0:20 offset1:28
	ds_read2_b32 v[38:39], v46 offset0:85 offset1:93
	ds_read2_b32 v[40:41], v46 offset0:150 offset1:158
	ds_read2_b32 v[42:43], v46 offset0:215 offset1:223
	s_waitcnt lgkmcnt(7)
	v_mov_b32_e32 v24, v30
	s_waitcnt lgkmcnt(6)
	v_mov_b32_e32 v25, v32
	s_waitcnt lgkmcnt(5)
	v_mov_b32_e32 v26, v28
	s_waitcnt lgkmcnt(4)
	v_mov_b32_e32 v27, v34
	v_pk_mul_f32 v[24:25], v[8:9], v[24:25]
	v_pk_mul_f32 v[26:27], v[10:11], v[26:27]
	v_cvt_pk_bf16_f32 v24, v24, v25
	v_cvt_pk_bf16_f32 v25, v26, v27
	s_waitcnt lgkmcnt(3)
	v_mov_b32_e32 v26, v36
	s_waitcnt lgkmcnt(2)
	v_mov_b32_e32 v27, v38
	s_waitcnt lgkmcnt(1)
	v_mov_b32_e32 v44, v40
	s_waitcnt lgkmcnt(0)
	v_mov_b32_e32 v45, v42
	v_pk_mul_f32 v[26:27], v[4:5], v[26:27]
	v_pk_mul_f32 v[44:45], v[6:7], v[44:45]
	v_or_b32_e32 v28, s3, v18
	v_cvt_pk_bf16_f32 v26, v26, v27
	v_cvt_pk_bf16_f32 v27, v44, v45
	v_lshlrev_b32_e32 v44, 12, v28
	v_mov_b32_e32 v45, v2
	v_lshl_add_u64 v[44:45], v[14:15], 0, v[44:45]
	v_mov_b32_e32 v32, v31
	v_mov_b32_e32 v34, v29
	global_store_dwordx4 v[44:45], v[24:27], off sc1
	v_mov_b32_e32 v38, v37
	v_mov_b32_e32 v42, v41
	v_pk_mul_f32 v[24:25], v[8:9], v[32:33]
	v_pk_mul_f32 v[26:27], v[10:11], v[34:35]
	v_cvt_pk_bf16_f32 v24, v24, v25
	v_cvt_pk_bf16_f32 v25, v26, v27
	v_pk_mul_f32 v[26:27], v[4:5], v[38:39]
	v_pk_mul_f32 v[28:29], v[6:7], v[42:43]
	v_cvt_pk_bf16_f32 v26, v26, v27
	v_cvt_pk_bf16_f32 v27, v28, v29
	v_or_b32_e32 v28, s3, v19
	v_lshlrev_b32_e32 v28, 12, v28
	v_mov_b32_e32 v29, v2
	v_lshl_add_u64 v[28:29], v[14:15], 0, v[28:29]
	ds_read2_b32 v[30:31], v16 offset0:32 offset1:40
	ds_read2_b32 v[32:33], v16 offset0:97 offset1:105
	global_store_dwordx4 v[28:29], v[24:27], off sc1
	ds_read2_b32 v[28:29], v16 offset0:162 offset1:170
	ds_read2_b32 v[34:35], v16 offset0:227 offset1:235
	ds_read2_b32 v[36:37], v46 offset0:36 offset1:44
	ds_read2_b32 v[38:39], v46 offset0:101 offset1:109
	ds_read2_b32 v[40:41], v46 offset0:166 offset1:174
	ds_read2_b32 v[42:43], v46 offset0:231 offset1:239
	s_waitcnt lgkmcnt(7)
; __device__ __forceinline__ unsigned pkbf(float lo, float hi) { typedef float f2_t __attribute__((ext_vector_type(2))); typedef __bf16 b2_t __attribute__((ext_vector_type(2))); f2_t v = {lo, hi}; b2_t b = __builtin_convertvector(v, b2_t); return __builtin_bit_cast(unsigned, b); }
; __device__ __forceinline__ void transpose_item(const float* W, int K, int N, bf16* WT, int k0, int n0, int dst_row0, const float* gain_k0, float* scr, int lane) {
;     ...
; #pragma unroll
;     for (int j = 0; j < 8; ++j) { const int n = (lane >> 3) + 8 * j; const float* s = scr + (8 * c) * 65 + n;
;         u32x4 o; o.x = pkbf(s[0 * 65] * g0.x, s[1 * 65] * g0.y); o.y = pkbf(s[2 * 65] * g0.z, s[3 * 65] * g0.w); o.z = pkbf(s[4 * 65] * g1.x, s[5 * 65] * g1.y); o.w = pkbf(s[6 * 65] * g1.z, s[7 * 65] * g1.w);
;         *(u32x4*)(WT + (size_t)(dst_row0 + n) * K + k0 + 8 * c) = o; }
;     asm volatile("s_waitcnt lgkmcnt(0)" ::: "memory");
	v_mov_b32_e32 v24, v30
	s_waitcnt lgkmcnt(6)
	v_mov_b32_e32 v25, v32
	s_waitcnt lgkmcnt(5)
	v_mov_b32_e32 v26, v28
	s_waitcnt lgkmcnt(4)
	v_mov_b32_e32 v27, v34
	v_pk_mul_f32 v[24:25], v[8:9], v[24:25]
	v_pk_mul_f32 v[26:27], v[10:11], v[26:27]
	v_cvt_pk_bf16_f32 v24, v24, v25
	v_cvt_pk_bf16_f32 v25, v26, v27
	s_waitcnt lgkmcnt(3)
	v_mov_b32_e32 v26, v36
	s_waitcnt lgkmcnt(2)
	v_mov_b32_e32 v27, v38
	s_waitcnt lgkmcnt(1)
	v_mov_b32_e32 v44, v40
	s_waitcnt lgkmcnt(0)
	v_mov_b32_e32 v45, v42
	v_pk_mul_f32 v[26:27], v[4:5], v[26:27]
	v_pk_mul_f32 v[44:45], v[6:7], v[44:45]
	v_or_b32_e32 v28, s3, v20
	v_cvt_pk_bf16_f32 v26, v26, v27
	v_cvt_pk_bf16_f32 v27, v44, v45
	v_lshlrev_b32_e32 v44, 12, v28
	v_mov_b32_e32 v45, v2
	v_lshl_add_u64 v[44:45], v[14:15], 0, v[44:45]
	v_mov_b32_e32 v32, v31
	v_mov_b32_e32 v34, v29
	global_store_dwordx4 v[44:45], v[24:27], off sc1
	v_mov_b32_e32 v38, v37
	v_mov_b32_e32 v42, v41
	v_pk_mul_f32 v[24:25], v[8:9], v[32:33]
	v_pk_mul_f32 v[26:27], v[10:11], v[34:35]
	v_cvt_pk_bf16_f32 v24, v24, v25
	v_cvt_pk_bf16_f32 v25, v26, v27
	v_pk_mul_f32 v[26:27], v[4:5], v[38:39]
	v_pk_mul_f32 v[28:29], v[6:7], v[42:43]
	v_cvt_pk_bf16_f32 v26, v26, v27
	v_cvt_pk_bf16_f32 v27, v28, v29
	v_or_b32_e32 v28, s3, v21
	v_lshlrev_b32_e32 v28, 12, v28
	v_mov_b32_e32 v29, v2
	v_lshl_add_u64 v[28:29], v[14:15], 0, v[28:29]
	ds_read2_b32 v[30:31], v16 offset0:48 offset1:56
	ds_read2_b32 v[32:33], v16 offset0:113 offset1:121
	global_store_dwordx4 v[28:29], v[24:27], off sc1
	ds_read2_b32 v[28:29], v16 offset0:178 offset1:186
	ds_read2_b32 v[34:35], v16 offset0:243 offset1:251
	ds_read2_b32 v[36:37], v46 offset0:52 offset1:60
	ds_read2_b32 v[38:39], v46 offset0:117 offset1:125
	ds_read2_b32 v[40:41], v46 offset0:182 offset1:190
	ds_read2_b32 v[42:43], v46 offset0:247 offset1:255
	s_waitcnt lgkmcnt(7)
	v_mov_b32_e32 v24, v30
	s_waitcnt lgkmcnt(6)
	v_mov_b32_e32 v25, v32
	s_waitcnt lgkmcnt(5)
	v_mov_b32_e32 v26, v28
	s_waitcnt lgkmcnt(4)
	v_mov_b32_e32 v27, v34
	v_pk_mul_f32 v[24:25], v[8:9], v[24:25]
	v_pk_mul_f32 v[26:27], v[10:11], v[26:27]
	v_cvt_pk_bf16_f32 v24, v24, v25
	v_cvt_pk_bf16_f32 v25, v26, v27
	s_waitcnt lgkmcnt(3)
	v_mov_b32_e32 v26, v36
	s_waitcnt lgkmcnt(2)
	v_mov_b32_e32 v27, v38
	v_mov_b32_e32 v32, v31
	v_mov_b32_e32 v34, v29
	v_mov_b32_e32 v38, v37
	v_pk_mul_f32 v[26:27], v[4:5], v[26:27]
	s_waitcnt lgkmcnt(0)
	v_mov_b32_e32 v45, v42
	v_pk_mul_f32 v[8:9], v[8:9], v[32:33]
	v_pk_mul_f32 v[10:11], v[10:11], v[34:35]
	v_pk_mul_f32 v[4:5], v[4:5], v[38:39]
	v_mov_b32_e32 v42, v41
	v_mov_b32_e32 v44, v40
	v_cvt_pk_bf16_f32 v8, v8, v9
	v_cvt_pk_bf16_f32 v9, v10, v11
	v_cvt_pk_bf16_f32 v10, v4, v5
	v_pk_mul_f32 v[4:5], v[6:7], v[42:43]
	v_pk_mul_f32 v[44:45], v[6:7], v[44:45]
	v_or_b32_e32 v28, s3, v22
	v_cvt_pk_bf16_f32 v11, v4, v5
	v_or_b32_e32 v4, s3, v23
	v_cvt_pk_bf16_f32 v26, v26, v27
	v_cvt_pk_bf16_f32 v27, v44, v45
	v_lshlrev_b32_e32 v44, 12, v28
	v_mov_b32_e32 v45, v2
	v_lshlrev_b32_e32 v4, 12, v4
	v_mov_b32_e32 v5, v2
	v_lshl_add_u64 v[44:45], v[14:15], 0, v[44:45]
	v_lshl_add_u64 v[4:5], v[14:15], 0, v[4:5]
	global_store_dwordx4 v[44:45], v[24:27], off sc1
	global_store_dwordx4 v[4:5], v[8:11], off sc1
	s_waitcnt lgkmcnt(0)

; __device__ __forceinline__ unsigned pkbf(float lo, float hi) { typedef float f2_t __attribute__((ext_vector_type(2))); typedef __bf16 b2_t __attribute__((ext_vector_type(2))); f2_t v = {lo, hi}; b2_t b = __builtin_convertvector(v, b2_t); return __builtin_bit_cast(unsigned, b); }
; __device__ __forceinline__ void transpose_item(const float* W, int K, int N, bf16* WT, int k0, int n0, int dst_row0, const float* gain_k0, float* scr, int lane) {
;     ...
; #pragma unroll
;     for (int j = 0; j < 8; ++j) { const int n = (lane >> 3) + 8 * j; const float* s = scr + (8 * c) * 65 + n;
;         u32x4 o; o.x = pkbf(s[0 * 65] * g0.x, s[1 * 65] * g0.y); o.y = pkbf(s[2 * 65] * g0.z, s[3 * 65] * g0.w); o.z = pkbf(s[4 * 65] * g1.x, s[5 * 65] * g1.y); o.w = pkbf(s[6 * 65] * g1.z, s[7 * 65] * g1.w);
;         *(u32x4*)(WT + (size_t)(dst_row0 + n) * K + k0 + 8 * c) = o; }
;     asm volatile("s_waitcnt lgkmcnt(0)" ::: "memory");
; __device__ __forceinline__ void convert_items(const Args& A, unsigned char* ws, int g0, int g1, int w, int nw, float* scr, int lane) {
;     ...
;         if (r < I_G) { const int nb = DFF / 64, kb = r / nb, n0 = 64 * (r % nb); transpose_item(A.w_gate + (size_t)l * DM * DFF, DM, DFF, (bf16*)(ws + WS_WGU + l * SZ_WGU), 64 * kb, n0, 256 * (n0 / 128) + (n0 % 128), A.norm2_g + l * DM + 64 * kb, scr, lane); continue; } r -= I_G;
.LBB0_238:
	ds_read2_b32 v[28:29], v16 offset1:8
	ds_read2_b32 v[30:31], v16 offset0:65 offset1:73
	ds_read2_b32 v[32:33], v16 offset0:130 offset1:138
	ds_read2_b32 v[34:35], v16 offset0:195 offset1:203
	v_add_u32_e32 v46, 0x400, v16
	s_lshl_b32 s4, s3, 6
	v_readlane_b32 s5, v249, 1
	ds_read2_b32 v[36:37], v46 offset0:4 offset1:12
	ds_read2_b32 v[38:39], v46 offset0:69 offset1:77
	ds_read2_b32 v[40:41], v46 offset0:134 offset1:142
	ds_read2_b32 v[42:43], v46 offset0:199 offset1:207
	s_add_u32 s5, s5, s12
	v_readlane_b32 s12, v249, 2
	s_addc_u32 s7, s12, s7
	s_lshl_b32 s3, s3, 7
	s_and_b32 s3, s3, 0x3f00
	s_and_b32 s4, s4, 64
	s_waitcnt lgkmcnt(7)
	v_mov_b32_e32 v24, v28
	s_waitcnt lgkmcnt(6)
	v_mov_b32_e32 v25, v30
	s_waitcnt lgkmcnt(5)
	v_mov_b32_e32 v26, v32
	s_waitcnt lgkmcnt(4)
	v_mov_b32_e32 v27, v34
	s_or_b32 s3, s3, s4
	s_lshl_b32 s4, s13, 1
	s_waitcnt vmcnt(1)
	v_pk_mul_f32 v[24:25], v[8:9], v[24:25]
	v_pk_mul_f32 v[26:27], v[10:11], v[26:27]
	s_add_u32 s4, s5, s4
	v_cvt_pk_bf16_f32 v24, v24, v25
	v_cvt_pk_bf16_f32 v25, v26, v27
	s_waitcnt lgkmcnt(3)
	v_mov_b32_e32 v26, v36
	s_waitcnt lgkmcnt(2)
	v_mov_b32_e32 v27, v38
	s_waitcnt lgkmcnt(1)
	v_mov_b32_e32 v44, v40
	s_waitcnt lgkmcnt(0)
	v_mov_b32_e32 v45, v42
	s_addc_u32 s5, s7, 0
	v_lshlrev_b32_e32 v14, 1, v12
	v_mov_b32_e32 v15, v2
	s_waitcnt vmcnt(0)
	v_pk_mul_f32 v[26:27], v[4:5], v[26:27]
	v_pk_mul_f32 v[44:45], v[6:7], v[44:45]
	v_or_b32_e32 v28, s3, v13
	v_lshl_add_u64 v[14:15], s[4:5], 0, v[14:15]
	v_cvt_pk_bf16_f32 v26, v26, v27
	v_cvt_pk_bf16_f32 v27, v44, v45
	v_lshlrev_b32_e32 v44, 12, v28
	v_mov_b32_e32 v45, v2
	v_lshl_add_u64 v[44:45], v[14:15], 0, v[44:45]
	v_mov_b32_e32 v30, v29
	v_mov_b32_e32 v34, v33
	global_store_dwordx4 v[44:45], v[24:27], off sc1
	v_mov_b32_e32 v38, v37
	v_mov_b32_e32 v42, v41
	v_pk_mul_f32 v[24:25], v[8:9], v[30:31]
	v_pk_mul_f32 v[26:27], v[10:11], v[34:35]
	v_cvt_pk_bf16_f32 v24, v24, v25
	v_cvt_pk_bf16_f32 v25, v26, v27
	v_pk_mul_f32 v[26:27], v[4:5], v[38:39]
	v_pk_mul_f32 v[28:29], v[6:7], v[42:43]
	v_cvt_pk_bf16_f32 v26, v26, v27
	v_cvt_pk_bf16_f32 v27, v28, v29
	v_or_b32_e32 v28, s3, v17
	v_lshlrev_b32_e32 v28, 12, v28
	v_mov_b32_e32 v29, v2
	v_lshl_add_u64 v[28:29], v[14:15], 0, v[28:29]
	ds_read2_b32 v[30:31], v16 offset0:16 offset1:24
	ds_read2_b32 v[32:33], v16 offset0:81 offset1:89
	global_store_dwordx4 v[28:29], v[24:27], off sc1
	ds_read2_b32 v[28:29], v16 offset0:146 offset1:154
	ds_read2_b32 v[34:35], v16 offset0:211 offset1:219
	ds_read2_b32 v[36:37], v46 offset0:20 offset1:28
	ds_read2_b32 v[38:39], v46 offset0:85 offset1:93
	ds_read2_b32 v[40:41], v46 offset0:150 offset1:158
	ds_read2_b32 v[42:43], v46 offset0:215 offset1:223
	s_waitcnt lgkmcnt(7)
	v_mov_b32_e32 v24, v30
	s_waitcnt lgkmcnt(6)
	v_mov_b32_e32 v25, v32
	s_waitcnt lgkmcnt(5)
	v_mov_b32_e32 v26, v28
	s_waitcnt lgkmcnt(4)
	v_mov_b32_e32 v27, v34
	v_pk_mul_f32 v[24:25], v[8:9], v[24:25]
	v_pk_mul_f32 v[26:27], v[10:11], v[26:27]
	v_cvt_pk_bf16_f32 v24, v24, v25
	v_cvt_pk_bf16_f32 v25, v26, v27
	s_waitcnt lgkmcnt(3)
	v_mov_b32_e32 v26, v36
	s_waitcnt lgkmcnt(2)
	v_mov_b32_e32 v27, v38
	s_waitcnt lgkmcnt(1)
	v_mov_b32_e32 v44, v40
	s_waitcnt lgkmcnt(0)
	v_mov_b32_e32 v45, v42
	v_pk_mul_f32 v[26:27], v[4:5], v[26:27]
	v_pk_mul_f32 v[44:45], v[6:7], v[44:45]
	v_or_b32_e32 v28, s3, v18
	v_cvt_pk_bf16_f32 v26, v26, v27
	v_cvt_pk_bf16_f32 v27, v44, v45
	v_lshlrev_b32_e32 v44, 12, v28
	v_mov_b32_e32 v45, v2
	v_lshl_add_u64 v[44:45], v[14:15], 0, v[44:45]
	v_mov_b32_e32 v32, v31
	v_mov_b32_e32 v34, v29
	global_store_dwordx4 v[44:45], v[24:27], off sc1
	v_mov_b32_e32 v38, v37
	v_mov_b32_e32 v42, v41
	v_pk_mul_f32 v[24:25], v[8:9], v[32:33]
	v_pk_mul_f32 v[26:27], v[10:11], v[34:35]
	v_cvt_pk_bf16_f32 v24, v24, v25
	v_cvt_pk_bf16_f32 v25, v26, v27
	v_pk_mul_f32 v[26:27], v[4:5], v[38:39]
	v_pk_mul_f32 v[28:29], v[6:7], v[42:43]
	v_cvt_pk_bf16_f32 v26, v26, v27
	v_cvt_pk_bf16_f32 v27, v28, v29
	v_or_b32_e32 v28, s3, v19
	v_lshlrev_b32_e32 v28, 12, v28
	v_mov_b32_e32 v29, v2
	v_lshl_add_u64 v[28:29], v[14:15], 0, v[28:29]
	ds_read2_b32 v[30:31], v16 offset0:32 offset1:40
	ds_read2_b32 v[32:33], v16 offset0:97 offset1:105
	global_store_dwordx4 v[28:29], v[24:27], off sc1
	ds_read2_b32 v[28:29], v16 offset0:162 offset1:170
	ds_read2_b32 v[34:35], v16 offset0:227 offset1:235
	ds_read2_b32 v[36:37], v46 offset0:36 offset1:44
	ds_read2_b32 v[38:39], v46 offset0:101 offset1:109
	ds_read2_b32 v[40:41], v46 offset0:166 offset1:174
	ds_read2_b32 v[42:43], v46 offset0:231 offset1:239
	s_waitcnt lgkmcnt(7)
; __device__ __forceinline__ unsigned pkbf(float lo, float hi) { typedef float f2_t __attribute__((ext_vector_type(2))); typedef __bf16 b2_t __attribute__((ext_vector_type(2))); f2_t v = {lo, hi}; b2_t b = __builtin_convertvector(v, b2_t); return __builtin_bit_cast(unsigned, b); }
; __device__ __forceinline__ void transpose_item(const float* W, int K, int N, bf16* WT, int k0, int n0, int dst_row0, const float* gain_k0, float* scr, int lane) {
;     ...
; #pragma unroll
;     for (int j = 0; j < 8; ++j) { const int n = (lane >> 3) + 8 * j; const float* s = scr + (8 * c) * 65 + n;
;         u32x4 o; o.x = pkbf(s[0 * 65] * g0.x, s[1 * 65] * g0.y); o.y = pkbf(s[2 * 65] * g0.z, s[3 * 65] * g0.w); o.z = pkbf(s[4 * 65] * g1.x, s[5 * 65] * g1.y); o.w = pkbf(s[6 * 65] * g1.z, s[7 * 65] * g1.w);
;         *(u32x4*)(WT + (size_t)(dst_row0 + n) * K + k0 + 8 * c) = o; }
;     asm volatile("s_waitcnt lgkmcnt(0)" ::: "memory");
	v_mov_b32_e32 v24, v30
	s_waitcnt lgkmcnt(6)
	v_mov_b32_e32 v25, v32
	s_waitcnt lgkmcnt(5)
	v_mov_b32_e32 v26, v28
	s_waitcnt lgkmcnt(4)
	v_mov_b32_e32 v27, v34
	v_pk_mul_f32 v[24:25], v[8:9], v[24:25]
	v_pk_mul_f32 v[26:27], v[10:11], v[26:27]
	v_cvt_pk_bf16_f32 v24, v24, v25
	v_cvt_pk_bf16_f32 v25, v26, v27
	s_waitcnt lgkmcnt(3)
	v_mov_b32_e32 v26, v36
	s_waitcnt lgkmcnt(2)
	v_mov_b32_e32 v27, v38
	s_waitcnt lgkmcnt(1)
	v_mov_b32_e32 v44, v40
	s_waitcnt lgkmcnt(0)
	v_mov_b32_e32 v45, v42
	v_pk_mul_f32 v[26:27], v[4:5], v[26:27]
	v_pk_mul_f32 v[44:45], v[6:7], v[44:45]
	v_or_b32_e32 v28, s3, v20
	v_cvt_pk_bf16_f32 v26, v26, v27
	v_cvt_pk_bf16_f32 v27, v44, v45
	v_lshlrev_b32_e32 v44, 12, v28
	v_mov_b32_e32 v45, v2
	v_lshl_add_u64 v[44:45], v[14:15], 0, v[44:45]
	v_mov_b32_e32 v32, v31
	v_mov_b32_e32 v34, v29
	global_store_dwordx4 v[44:45], v[24:27], off sc1
	v_mov_b32_e32 v38, v37
	v_mov_b32_e32 v42, v41
	v_pk_mul_f32 v[24:25], v[8:9], v[32:33]
	v_pk_mul_f32 v[26:27], v[10:11], v[34:35]
	v_cvt_pk_bf16_f32 v24, v24, v25
	v_cvt_pk_bf16_f32 v25, v26, v27
	v_pk_mul_f32 v[26:27], v[4:5], v[38:39]
	v_pk_mul_f32 v[28:29], v[6:7], v[42:43]
	v_cvt_pk_bf16_f32 v26, v26, v27
	v_cvt_pk_bf16_f32 v27, v28, v29
	v_or_b32_e32 v28, s3, v21
	v_lshlrev_b32_e32 v28, 12, v28
	v_mov_b32_e32 v29, v2
	v_lshl_add_u64 v[28:29], v[14:15], 0, v[28:29]
	ds_read2_b32 v[30:31], v16 offset0:48 offset1:56
	ds_read2_b32 v[32:33], v16 offset0:113 offset1:121
	global_store_dwordx4 v[28:29], v[24:27], off sc1
	ds_read2_b32 v[28:29], v16 offset0:178 offset1:186
	ds_read2_b32 v[34:35], v16 offset0:243 offset1:251
	ds_read2_b32 v[36:37], v46 offset0:52 offset1:60
	ds_read2_b32 v[38:39], v46 offset0:117 offset1:125
	ds_read2_b32 v[40:41], v46 offset0:182 offset1:190
	ds_read2_b32 v[42:43], v46 offset0:247 offset1:255
	s_waitcnt lgkmcnt(7)
	v_mov_b32_e32 v24, v30
	s_waitcnt lgkmcnt(6)
	v_mov_b32_e32 v25, v32
	s_waitcnt lgkmcnt(5)
	v_mov_b32_e32 v26, v28
	s_waitcnt lgkmcnt(4)
	v_mov_b32_e32 v27, v34
	v_pk_mul_f32 v[24:25], v[8:9], v[24:25]
	v_pk_mul_f32 v[26:27], v[10:11], v[26:27]
	v_cvt_pk_bf16_f32 v24, v24, v25
	v_cvt_pk_bf16_f32 v25, v26, v27
	s_waitcnt lgkmcnt(3)
	v_mov_b32_e32 v26, v36
	s_waitcnt lgkmcnt(2)
	v_mov_b32_e32 v27, v38
	v_mov_b32_e32 v32, v31
	v_mov_b32_e32 v34, v29
	v_mov_b32_e32 v38, v37
	v_pk_mul_f32 v[26:27], v[4:5], v[26:27]
	s_waitcnt lgkmcnt(0)
	v_mov_b32_e32 v45, v42
	v_pk_mul_f32 v[8:9], v[8:9], v[32:33]
	v_pk_mul_f32 v[10:11], v[10:11], v[34:35]
	v_pk_mul_f32 v[4:5], v[4:5], v[38:39]
	v_mov_b32_e32 v42, v41
	v_mov_b32_e32 v44, v40
	v_cvt_pk_bf16_f32 v8, v8, v9
	v_cvt_pk_bf16_f32 v9, v10, v11
	v_cvt_pk_bf16_f32 v10, v4, v5
	v_pk_mul_f32 v[4:5], v[6:7], v[42:43]
	v_pk_mul_f32 v[44:45], v[6:7], v[44:45]
	v_or_b32_e32 v28, s3, v22
	v_cvt_pk_bf16_f32 v11, v4, v5
	v_or_b32_e32 v4, s3, v23
	v_cvt_pk_bf16_f32 v26, v26, v27
	v_cvt_pk_bf16_f32 v27, v44, v45
	v_lshlrev_b32_e32 v44, 12, v28
	v_mov_b32_e32 v45, v2
	v_lshlrev_b32_e32 v4, 12, v4
	v_mov_b32_e32 v5, v2
	v_lshl_add_u64 v[44:45], v[14:15], 0, v[44:45]
	v_lshl_add_u64 v[4:5], v[14:15], 0, v[4:5]
	global_store_dwordx4 v[44:45], v[24:27], off sc1
	global_store_dwordx4 v[4:5], v[8:11], off sc1
	s_waitcnt lgkmcnt(0)

; __device__ __forceinline__ unsigned pkbf(float lo, float hi) { typedef float f2_t __attribute__((ext_vector_type(2))); typedef __bf16 b2_t __attribute__((ext_vector_type(2))); f2_t v = {lo, hi}; b2_t b = __builtin_convertvector(v, b2_t); return __builtin_bit_cast(unsigned, b); }
; __device__ __forceinline__ void transpose_item(const float* W, int K, int N, bf16* WT, int k0, int n0, int dst_row0, const float* gain_k0, float* scr, int lane) {
;     ...
; #pragma unroll
;     for (int j = 0; j < 8; ++j) { const int n = (lane >> 3) + 8 * j; const float* s = scr + (8 * c) * 65 + n;
;         u32x4 o; o.x = pkbf(s[0 * 65] * g0.x, s[1 * 65] * g0.y); o.y = pkbf(s[2 * 65] * g0.z, s[3 * 65] * g0.w); o.z = pkbf(s[4 * 65] * g1.x, s[5 * 65] * g1.y); o.w = pkbf(s[6 * 65] * g1.z, s[7 * 65] * g1.w);
;         *(u32x4*)(WT + (size_t)(dst_row0 + n) * K + k0 + 8 * c) = o; }
;     asm volatile("s_waitcnt lgkmcnt(0)" ::: "memory");
; __device__ __forceinline__ void convert_items(const Args& A, unsigned char* ws, int g0, int g1, int w, int nw, float* scr, int lane) {
;     ...
;         if (r < I_OUT) { const int nb = DM / 64, kb = r / nb, n0 = 64 * (r % nb); transpose_item(A.w_out + (size_t)l * DM * DM, DM, DM, (bf16*)(ws + WS_WOUT + l * SZ_WOUT), 64 * kb, n0, n0, (kb < 16 ? A.out_norm_a + l * 1024 + 64 * kb : A.out_norm_b + l * 1024 + 64 * (kb - 16)), scr, lane); continue; } r -= I_OUT;
.LBB0_244:
	ds_read2_b32 v[28:29], v16 offset1:8
	ds_read2_b32 v[30:31], v16 offset0:65 offset1:73
	ds_read2_b32 v[32:33], v16 offset0:130 offset1:138
	ds_read2_b32 v[34:35], v16 offset0:195 offset1:203
	v_add_u32_e32 v46, 0x400, v16
	ds_read2_b32 v[36:37], v46 offset0:4 offset1:12
	ds_read2_b32 v[38:39], v46 offset0:69 offset1:77
	ds_read2_b32 v[40:41], v46 offset0:134 offset1:142
	ds_read2_b32 v[42:43], v46 offset0:199 offset1:207
	s_lshl_b64 s[4:5], s[2:3], 23
	v_readlane_b32 s3, v249, 3
	s_add_u32 s3, s3, s4
	v_readlane_b32 s4, v249, 4
	s_waitcnt lgkmcnt(7)
	v_mov_b32_e32 v24, v28
	s_waitcnt lgkmcnt(6)
	v_mov_b32_e32 v25, v30
	s_waitcnt lgkmcnt(5)
	v_mov_b32_e32 v26, v32
	s_waitcnt lgkmcnt(4)
	v_mov_b32_e32 v27, v34
	s_addc_u32 s5, s4, s5
	s_lshl_b32 s4, s76, 1
	s_waitcnt vmcnt(1)
	v_pk_mul_f32 v[24:25], v[4:5], v[24:25]
	v_pk_mul_f32 v[26:27], v[6:7], v[26:27]
	s_add_u32 s4, s3, s4
	v_cvt_pk_bf16_f32 v24, v24, v25
	v_cvt_pk_bf16_f32 v25, v26, v27
	s_waitcnt lgkmcnt(3)
	v_mov_b32_e32 v26, v36
	s_waitcnt lgkmcnt(2)
	v_mov_b32_e32 v27, v38
	s_waitcnt lgkmcnt(1)
	v_mov_b32_e32 v44, v40
	s_waitcnt lgkmcnt(0)
	v_mov_b32_e32 v45, v42
	s_addc_u32 s5, s5, 0
	v_lshlrev_b32_e32 v14, 1, v12
	v_mov_b32_e32 v15, v2
	s_waitcnt vmcnt(0)
	v_pk_mul_f32 v[26:27], v[8:9], v[26:27]
	v_pk_mul_f32 v[44:45], v[10:11], v[44:45]
	v_or_b32_e32 v28, s7, v13
	v_lshl_add_u64 v[14:15], s[4:5], 0, v[14:15]
	v_cvt_pk_bf16_f32 v26, v26, v27
	v_cvt_pk_bf16_f32 v27, v44, v45
	v_lshlrev_b32_e32 v44, 12, v28
	v_mov_b32_e32 v45, v2
	v_lshl_add_u64 v[44:45], v[14:15], 0, v[44:45]
	v_mov_b32_e32 v30, v29
	v_mov_b32_e32 v34, v33
	global_store_dwordx4 v[44:45], v[24:27], off sc1
	v_mov_b32_e32 v38, v37
	v_mov_b32_e32 v42, v41
	v_pk_mul_f32 v[24:25], v[4:5], v[30:31]
	v_pk_mul_f32 v[26:27], v[6:7], v[34:35]
	v_cvt_pk_bf16_f32 v24, v24, v25
	v_cvt_pk_bf16_f32 v25, v26, v27
	v_pk_mul_f32 v[26:27], v[8:9], v[38:39]
	v_pk_mul_f32 v[28:29], v[10:11], v[42:43]
	v_cvt_pk_bf16_f32 v26, v26, v27
	v_cvt_pk_bf16_f32 v27, v28, v29
	v_or_b32_e32 v28, s7, v17
	v_lshlrev_b32_e32 v28, 12, v28
	v_mov_b32_e32 v29, v2
	v_lshl_add_u64 v[28:29], v[14:15], 0, v[28:29]
	ds_read2_b32 v[30:31], v16 offset0:16 offset1:24
	ds_read2_b32 v[32:33], v16 offset0:81 offset1:89
	global_store_dwordx4 v[28:29], v[24:27], off sc1
	ds_read2_b32 v[28:29], v16 offset0:146 offset1:154
	ds_read2_b32 v[34:35], v16 offset0:211 offset1:219
	ds_read2_b32 v[36:37], v46 offset0:20 offset1:28
	ds_read2_b32 v[38:39], v46 offset0:85 offset1:93
	ds_read2_b32 v[40:41], v46 offset0:150 offset1:158
	ds_read2_b32 v[42:43], v46 offset0:215 offset1:223
	s_waitcnt lgkmcnt(7)
	v_mov_b32_e32 v24, v30
	s_waitcnt lgkmcnt(6)
	v_mov_b32_e32 v25, v32
	s_waitcnt lgkmcnt(5)
	v_mov_b32_e32 v26, v28
	s_waitcnt lgkmcnt(4)
	v_mov_b32_e32 v27, v34
	v_pk_mul_f32 v[24:25], v[4:5], v[24:25]
	v_pk_mul_f32 v[26:27], v[6:7], v[26:27]
	v_cvt_pk_bf16_f32 v24, v24, v25
	v_cvt_pk_bf16_f32 v25, v26, v27
	s_waitcnt lgkmcnt(3)
	v_mov_b32_e32 v26, v36
	s_waitcnt lgkmcnt(2)
	v_mov_b32_e32 v27, v38
	s_waitcnt lgkmcnt(1)
	v_mov_b32_e32 v44, v40
	s_waitcnt lgkmcnt(0)
	v_mov_b32_e32 v45, v42
	v_pk_mul_f32 v[26:27], v[8:9], v[26:27]
	v_pk_mul_f32 v[44:45], v[10:11], v[44:45]
	v_or_b32_e32 v28, s7, v18
	v_cvt_pk_bf16_f32 v26, v26, v27
	v_cvt_pk_bf16_f32 v27, v44, v45
	v_lshlrev_b32_e32 v44, 12, v28
	v_mov_b32_e32 v45, v2
	v_lshl_add_u64 v[44:45], v[14:15], 0, v[44:45]
	v_mov_b32_e32 v32, v31
	v_mov_b32_e32 v34, v29
	global_store_dwordx4 v[44:45], v[24:27], off sc1
	v_mov_b32_e32 v38, v37
	v_mov_b32_e32 v42, v41
	v_pk_mul_f32 v[24:25], v[4:5], v[32:33]
	v_pk_mul_f32 v[26:27], v[6:7], v[34:35]
	v_cvt_pk_bf16_f32 v24, v24, v25
	v_cvt_pk_bf16_f32 v25, v26, v27
	v_pk_mul_f32 v[26:27], v[8:9], v[38:39]
	v_pk_mul_f32 v[28:29], v[10:11], v[42:43]
	v_cvt_pk_bf16_f32 v26, v26, v27
	v_cvt_pk_bf16_f32 v27, v28, v29
	v_or_b32_e32 v28, s7, v19
	v_lshlrev_b32_e32 v28, 12, v28
	v_mov_b32_e32 v29, v2
	v_lshl_add_u64 v[28:29], v[14:15], 0, v[28:29]
	ds_read2_b32 v[30:31], v16 offset0:32 offset1:40
	ds_read2_b32 v[32:33], v16 offset0:97 offset1:105
	global_store_dwordx4 v[28:29], v[24:27], off sc1
	ds_read2_b32 v[28:29], v16 offset0:162 offset1:170
	ds_read2_b32 v[34:35], v16 offset0:227 offset1:235
	ds_read2_b32 v[36:37], v46 offset0:36 offset1:44
	ds_read2_b32 v[38:39], v46 offset0:101 offset1:109
	ds_read2_b32 v[40:41], v46 offset0:166 offset1:174
	ds_read2_b32 v[42:43], v46 offset0:231 offset1:239
	s_waitcnt lgkmcnt(7)
; __device__ __forceinline__ unsigned pkbf(float lo, float hi) { typedef float f2_t __attribute__((ext_vector_type(2))); typedef __bf16 b2_t __attribute__((ext_vector_type(2))); f2_t v = {lo, hi}; b2_t b = __builtin_convertvector(v, b2_t); return __builtin_bit_cast(unsigned, b); }
; __device__ __forceinline__ void transpose_item(const float* W, int K, int N, bf16* WT, int k0, int n0, int dst_row0, const float* gain_k0, float* scr, int lane) {
;     ...
; #pragma unroll
;     for (int j = 0; j < 8; ++j) { const int n = (lane >> 3) + 8 * j; const float* s = scr + (8 * c) * 65 + n;
;         u32x4 o; o.x = pkbf(s[0 * 65] * g0.x, s[1 * 65] * g0.y); o.y = pkbf(s[2 * 65] * g0.z, s[3 * 65] * g0.w); o.z = pkbf(s[4 * 65] * g1.x, s[5 * 65] * g1.y); o.w = pkbf(s[6 * 65] * g1.z, s[7 * 65] * g1.w);
;         *(u32x4*)(WT + (size_t)(dst_row0 + n) * K + k0 + 8 * c) = o; }
;     asm volatile("s_waitcnt lgkmcnt(0)" ::: "memory");
	v_mov_b32_e32 v24, v30
	s_waitcnt lgkmcnt(6)
	v_mov_b32_e32 v25, v32
	s_waitcnt lgkmcnt(5)
	v_mov_b32_e32 v26, v28
	s_waitcnt lgkmcnt(4)
	v_mov_b32_e32 v27, v34
	v_pk_mul_f32 v[24:25], v[4:5], v[24:25]
	v_pk_mul_f32 v[26:27], v[6:7], v[26:27]
	v_cvt_pk_bf16_f32 v24, v24, v25
	v_cvt_pk_bf16_f32 v25, v26, v27
	s_waitcnt lgkmcnt(3)
	v_mov_b32_e32 v26, v36
	s_waitcnt lgkmcnt(2)
	v_mov_b32_e32 v27, v38
	s_waitcnt lgkmcnt(1)
	v_mov_b32_e32 v44, v40
	s_waitcnt lgkmcnt(0)
	v_mov_b32_e32 v45, v42
	v_pk_mul_f32 v[26:27], v[8:9], v[26:27]
	v_pk_mul_f32 v[44:45], v[10:11], v[44:45]
	v_or_b32_e32 v28, s7, v20
	v_cvt_pk_bf16_f32 v26, v26, v27
	v_cvt_pk_bf16_f32 v27, v44, v45
	v_lshlrev_b32_e32 v44, 12, v28
	v_mov_b32_e32 v45, v2
	v_lshl_add_u64 v[44:45], v[14:15], 0, v[44:45]
	v_mov_b32_e32 v32, v31
	v_mov_b32_e32 v34, v29
	global_store_dwordx4 v[44:45], v[24:27], off sc1
	v_mov_b32_e32 v38, v37
	v_mov_b32_e32 v42, v41
	v_pk_mul_f32 v[24:25], v[4:5], v[32:33]
	v_pk_mul_f32 v[26:27], v[6:7], v[34:35]
	v_cvt_pk_bf16_f32 v24, v24, v25
	v_cvt_pk_bf16_f32 v25, v26, v27
	v_pk_mul_f32 v[26:27], v[8:9], v[38:39]
	v_pk_mul_f32 v[28:29], v[10:11], v[42:43]
	v_cvt_pk_bf16_f32 v26, v26, v27
	v_cvt_pk_bf16_f32 v27, v28, v29
	v_or_b32_e32 v28, s7, v21
	v_lshlrev_b32_e32 v28, 12, v28
	v_mov_b32_e32 v29, v2
	v_lshl_add_u64 v[28:29], v[14:15], 0, v[28:29]
	ds_read2_b32 v[30:31], v16 offset0:48 offset1:56
	ds_read2_b32 v[32:33], v16 offset0:113 offset1:121
	global_store_dwordx4 v[28:29], v[24:27], off sc1
	ds_read2_b32 v[28:29], v16 offset0:178 offset1:186
	ds_read2_b32 v[34:35], v16 offset0:243 offset1:251
	ds_read2_b32 v[36:37], v46 offset0:52 offset1:60
	ds_read2_b32 v[38:39], v46 offset0:117 offset1:125
	ds_read2_b32 v[40:41], v46 offset0:182 offset1:190
	ds_read2_b32 v[42:43], v46 offset0:247 offset1:255
	s_waitcnt lgkmcnt(7)
	v_mov_b32_e32 v24, v30
	s_waitcnt lgkmcnt(6)
	v_mov_b32_e32 v25, v32
	s_waitcnt lgkmcnt(5)
	v_mov_b32_e32 v26, v28
	s_waitcnt lgkmcnt(4)
	v_mov_b32_e32 v27, v34
	v_pk_mul_f32 v[24:25], v[4:5], v[24:25]
	v_pk_mul_f32 v[26:27], v[6:7], v[26:27]
	v_mov_b32_e32 v32, v31
	v_mov_b32_e32 v34, v29
	v_cvt_pk_bf16_f32 v24, v24, v25
	v_cvt_pk_bf16_f32 v25, v26, v27
	s_waitcnt lgkmcnt(3)
	v_mov_b32_e32 v26, v36
	s_waitcnt lgkmcnt(2)
	v_mov_b32_e32 v27, v38
	s_waitcnt lgkmcnt(0)
	v_mov_b32_e32 v45, v42
	v_pk_mul_f32 v[4:5], v[4:5], v[32:33]
	v_pk_mul_f32 v[6:7], v[6:7], v[34:35]
	v_mov_b32_e32 v38, v37
	v_mov_b32_e32 v42, v41
	v_pk_mul_f32 v[26:27], v[8:9], v[26:27]
	v_mov_b32_e32 v44, v40
	v_cvt_pk_bf16_f32 v4, v4, v5
	v_cvt_pk_bf16_f32 v5, v6, v7
	v_pk_mul_f32 v[6:7], v[8:9], v[38:39]
	v_pk_mul_f32 v[8:9], v[10:11], v[42:43]
	v_pk_mul_f32 v[44:45], v[10:11], v[44:45]
	v_or_b32_e32 v28, s7, v22
	v_cvt_pk_bf16_f32 v6, v6, v7
	v_cvt_pk_bf16_f32 v7, v8, v9
	v_or_b32_e32 v8, s7, v23
	v_cvt_pk_bf16_f32 v26, v26, v27
	v_cvt_pk_bf16_f32 v27, v44, v45
	v_lshlrev_b32_e32 v44, 12, v28
	v_mov_b32_e32 v45, v2
	v_lshlrev_b32_e32 v8, 12, v8
	v_mov_b32_e32 v9, v2
	v_lshl_add_u64 v[44:45], v[14:15], 0, v[44:45]
	v_lshl_add_u64 v[8:9], v[14:15], 0, v[8:9]
	global_store_dwordx4 v[44:45], v[24:27], off sc1
	global_store_dwordx4 v[8:9], v[4:7], off sc1
	s_waitcnt lgkmcnt(0)
